# RWKV staging: one reciprocal per block for the 1/G chain (backward products) and packed sigmoid arguments; with GDN chain relocation
# baseline (speedup 1.0000x reference)
.LBB0_564:
	v_mov_b32_e32 v78, v75
	v_mov_b32_e32 v76, v77
	s_and_b32 s3, s40, 1
	v_add_u32_e32 v28, s72, v76
	v_ashrrev_i32_e32 v29, 31, v28
	v_lshlrev_b64 v[10:11], 2, v[28:29]
	s_and_b32 s3, s40, 1
	s_mov_b32 s0, 0x17800
	s_mov_b32 s1, 0x1b800
	s_cmp_eq_u32 s3, 0
	s_cselect_b32 s41, 0x11800, s0
	s_cselect_b32 s16, 0x23800, s1
	v_lshlrev_b32_e32 v26, 3, v78
	v_mul_u32_u24_e32 v166, 0x880, v78
	v_lshl_add_u32 v166, v76, 2, v166
	v_lshlrev_b32_e32 v167, 11, v78
	v_lshl_add_u32 v167, v76, 2, v167
	v_add_u32_e32 v167, s41, v167
	v_mov_b32_e32 v140, 1.0
	s_mov_b32 s6, 0xbfb8aa3b
	v_sub_f32_e32 v169, v106, v44
	v_sub_f32_e32 v170, v35, v46
	v_sub_f32_e32 v171, v34, v48
	v_fma_f32 v169, v169, v115, v44
	v_fma_f32 v170, v170, v116, v46
	v_fma_f32 v171, v171, v119, v48
	v_add_f32_e32 v200, v50, v117
	v_add_f32_e32 v201, v107, v118
	v_pk_mul_f32 v[200:201], v[200:201], s[6:7] op_sel_hi:[1,0]
	v_exp_f32_e32 v200, v200
	v_exp_f32_e32 v201, v201
	ds_write_b32 v167, v171 offset:0
	v_pk_add_f32 v[200:201], v[200:201], 1.0 op_sel_hi:[1,0]
	v_rcp_f32_e32 v200, v200
	v_rcp_f32_e32 v201, v201
	v_mul_f32_e32 v124, v170, v120
	v_mul_f32_e32 v201, 0xbf1b4598, v201
	v_add_f32_e32 v132, -1.0, v200
	v_mul_f32_e32 v201, 0x3fb8aa3b, v201
	v_fma_f32 v132, v121, v132, 1.0
	v_exp_f32_e32 v201, v201
	v_mul_f32_e32 v132, v170, v132
	v_mul_f32_e32 v150, v124, v124
	v_mul_f32_e32 v175, v169, v132
	v_mul_f32_e32 v141, v140, v201
	v_mul_f32_e32 v158, v122, v175
	v_mul_f32_e32 v169, v169, v141
	ds_write_b32 v166, v169 offset:17408
	v_sub_f32_e32 v169, v44, v1
	v_sub_f32_e32 v170, v46, v45
	v_sub_f32_e32 v171, v48, v47
	v_fma_f32 v169, v169, v115, v1
	v_fma_f32 v170, v170, v116, v45
	v_fma_f32 v171, v171, v119, v47
	v_add_f32_e32 v202, v51, v117
	v_add_f32_e32 v203, v108, v118
	v_pk_mul_f32 v[202:203], v[202:203], s[6:7] op_sel_hi:[1,0]
	v_exp_f32_e32 v202, v202
	v_exp_f32_e32 v203, v203
	ds_write_b32 v167, v171 offset:256
	v_pk_add_f32 v[202:203], v[202:203], 1.0 op_sel_hi:[1,0]
	v_rcp_f32_e32 v202, v202
	v_rcp_f32_e32 v203, v203
	v_mul_f32_e32 v125, v170, v120
	v_mul_f32_e32 v203, 0xbf1b4598, v203
	v_add_f32_e32 v133, -1.0, v202
	v_mul_f32_e32 v203, 0x3fb8aa3b, v203
	v_fma_f32 v133, v121, v133, 1.0
	v_exp_f32_e32 v203, v203
	v_mul_f32_e32 v133, v170, v133
	v_mul_f32_e32 v152, v125, v125
	v_mul_f32_e32 v175, v169, v133
	v_mul_f32_e32 v142, v141, v203
	v_mul_f32_e32 v160, v122, v175
	v_mul_f32_e32 v169, v169, v142
	ds_write_b32 v166, v169 offset:17680
	v_sub_f32_e32 v169, v1, v52
	v_sub_f32_e32 v170, v45, v54
	v_sub_f32_e32 v171, v47, v56
	v_fma_f32 v169, v169, v115, v52
	v_fma_f32 v170, v170, v116, v54
	v_fma_f32 v171, v171, v119, v56
	v_add_f32_e32 v204, v58, v117
	v_add_f32_e32 v205, v109, v118
	v_pk_mul_f32 v[204:205], v[204:205], s[6:7] op_sel_hi:[1,0]
	v_exp_f32_e32 v204, v204
	v_exp_f32_e32 v205, v205
	ds_write_b32 v167, v171 offset:512
	v_pk_add_f32 v[204:205], v[204:205], 1.0 op_sel_hi:[1,0]
	v_rcp_f32_e32 v204, v204
	v_rcp_f32_e32 v205, v205
	v_mul_f32_e32 v126, v170, v120
	v_mul_f32_e32 v205, 0xbf1b4598, v205
	v_add_f32_e32 v134, -1.0, v204
	v_mul_f32_e32 v205, 0x3fb8aa3b, v205
	v_fma_f32 v134, v121, v134, 1.0
	v_exp_f32_e32 v205, v205
	v_mul_f32_e32 v134, v170, v134
	v_mul_f32_e32 v151, v126, v126
	v_mul_f32_e32 v175, v169, v134
	v_mul_f32_e32 v143, v142, v205
	v_mul_f32_e32 v159, v122, v175
	v_mul_f32_e32 v169, v169, v143
	ds_write_b32 v166, v169 offset:17952
	v_sub_f32_e32 v169, v52, v49
	v_sub_f32_e32 v170, v54, v53
	v_sub_f32_e32 v171, v56, v55
	v_fma_f32 v169, v169, v115, v49
	v_fma_f32 v170, v170, v116, v53
	v_fma_f32 v171, v171, v119, v55
	v_add_f32_e32 v206, v57, v117
	v_add_f32_e32 v207, v110, v118
	v_pk_mul_f32 v[206:207], v[206:207], s[6:7] op_sel_hi:[1,0]
	v_exp_f32_e32 v206, v206
	v_exp_f32_e32 v207, v207
	ds_write_b32 v167, v171 offset:768
	v_pk_add_f32 v[206:207], v[206:207], 1.0 op_sel_hi:[1,0]
	v_rcp_f32_e32 v206, v206
	v_rcp_f32_e32 v207, v207
	v_mul_f32_e32 v127, v170, v120
	v_mul_f32_e32 v207, 0xbf1b4598, v207
	v_add_f32_e32 v135, -1.0, v206
	v_mul_f32_e32 v207, 0x3fb8aa3b, v207
	v_fma_f32 v135, v121, v135, 1.0
	v_exp_f32_e32 v207, v207
	v_mul_f32_e32 v135, v170, v135
	v_mul_f32_e32 v153, v127, v127
	v_mul_f32_e32 v175, v169, v135
	v_mul_f32_e32 v144, v143, v207
	v_mul_f32_e32 v161, v122, v175
	v_mul_f32_e32 v169, v169, v144
	ds_write_b32 v166, v169 offset:18224
	v_sub_f32_e32 v169, v49, v60
	v_sub_f32_e32 v170, v53, v62
	v_sub_f32_e32 v171, v55, v64
	v_fma_f32 v169, v169, v115, v60
	v_fma_f32 v170, v170, v116, v62
	v_fma_f32 v171, v171, v119, v64
	v_add_f32_e32 v208, v66, v117
	v_add_f32_e32 v209, v111, v118
	v_pk_mul_f32 v[208:209], v[208:209], s[6:7] op_sel_hi:[1,0]
	v_exp_f32_e32 v208, v208
	v_exp_f32_e32 v209, v209
	ds_write_b32 v167, v171 offset:1024
	v_pk_add_f32 v[208:209], v[208:209], 1.0 op_sel_hi:[1,0]
	v_rcp_f32_e32 v208, v208
	v_rcp_f32_e32 v209, v209
	v_mul_f32_e32 v128, v170, v120
	v_mul_f32_e32 v209, 0xbf1b4598, v209
	v_add_f32_e32 v136, -1.0, v208
	v_mul_f32_e32 v209, 0x3fb8aa3b, v209
	v_fma_f32 v136, v121, v136, 1.0
	v_exp_f32_e32 v209, v209
	v_mul_f32_e32 v136, v170, v136
	v_mul_f32_e32 v154, v128, v128
	v_mul_f32_e32 v175, v169, v136
	v_mul_f32_e32 v145, v144, v209
	v_mul_f32_e32 v162, v122, v175
	v_mul_f32_e32 v169, v169, v145
	ds_write_b32 v166, v169 offset:18496
	v_sub_f32_e32 v169, v60, v59
	v_sub_f32_e32 v170, v62, v61
	v_sub_f32_e32 v171, v64, v63
	v_fma_f32 v169, v169, v115, v59
	v_fma_f32 v170, v170, v116, v61
	v_fma_f32 v171, v171, v119, v63
	v_add_f32_e32 v210, v65, v117
	v_add_f32_e32 v211, v112, v118
	v_pk_mul_f32 v[210:211], v[210:211], s[6:7] op_sel_hi:[1,0]
	v_exp_f32_e32 v210, v210
	v_exp_f32_e32 v211, v211
	ds_write_b32 v167, v171 offset:1280
	v_pk_add_f32 v[210:211], v[210:211], 1.0 op_sel_hi:[1,0]
	v_rcp_f32_e32 v210, v210
	v_rcp_f32_e32 v211, v211
	v_mul_f32_e32 v129, v170, v120
	v_mul_f32_e32 v211, 0xbf1b4598, v211
	v_add_f32_e32 v137, -1.0, v210
	v_mul_f32_e32 v211, 0x3fb8aa3b, v211
	v_fma_f32 v137, v121, v137, 1.0
	v_exp_f32_e32 v211, v211
	v_mul_f32_e32 v137, v170, v137
	v_mul_f32_e32 v156, v129, v129
	v_mul_f32_e32 v175, v169, v137
	v_mul_f32_e32 v146, v145, v211
	v_mul_f32_e32 v164, v122, v175
	v_mul_f32_e32 v169, v169, v146
	ds_write_b32 v166, v169 offset:18768
	v_sub_f32_e32 v169, v59, v67
	v_sub_f32_e32 v170, v61, v69
	v_sub_f32_e32 v171, v63, v71
	v_fma_f32 v169, v169, v115, v67
	v_fma_f32 v170, v170, v116, v69
	v_fma_f32 v171, v171, v119, v71
	v_add_f32_e32 v212, v74, v117
	v_add_f32_e32 v213, v113, v118
	v_pk_mul_f32 v[212:213], v[212:213], s[6:7] op_sel_hi:[1,0]
	v_exp_f32_e32 v212, v212
	v_exp_f32_e32 v213, v213
	ds_write_b32 v167, v171 offset:1536
	v_pk_add_f32 v[212:213], v[212:213], 1.0 op_sel_hi:[1,0]
	v_rcp_f32_e32 v212, v212
	v_rcp_f32_e32 v213, v213
	v_mul_f32_e32 v130, v170, v120
	v_mul_f32_e32 v213, 0xbf1b4598, v213
	v_add_f32_e32 v138, -1.0, v212
	v_mul_f32_e32 v213, 0x3fb8aa3b, v213
	v_fma_f32 v138, v121, v138, 1.0
	v_exp_f32_e32 v213, v213
	v_mul_f32_e32 v138, v170, v138
	v_mul_f32_e32 v155, v130, v130
	v_mul_f32_e32 v175, v169, v138
	v_mul_f32_e32 v147, v146, v213
	v_mul_f32_e32 v163, v122, v175
	v_mul_f32_e32 v169, v169, v147
	ds_write_b32 v166, v169 offset:19040
	v_sub_f32_e32 v169, v67, v68
	v_sub_f32_e32 v170, v69, v70
	v_sub_f32_e32 v171, v71, v72
	v_fma_f32 v169, v169, v115, v68
	v_fma_f32 v170, v170, v116, v70
	v_fma_f32 v171, v171, v119, v72
	v_add_f32_e32 v214, v73, v117
	v_add_f32_e32 v215, v114, v118
	v_pk_mul_f32 v[214:215], v[214:215], s[6:7] op_sel_hi:[1,0]
	v_exp_f32_e32 v214, v214
	v_exp_f32_e32 v215, v215
	ds_write_b32 v167, v171 offset:1792
	v_pk_add_f32 v[214:215], v[214:215], 1.0 op_sel_hi:[1,0]
	v_rcp_f32_e32 v214, v214
	v_rcp_f32_e32 v215, v215
	v_mul_f32_e32 v131, v170, v120
	v_mul_f32_e32 v215, 0xbf1b4598, v215
	v_add_f32_e32 v139, -1.0, v214
	v_mul_f32_e32 v215, 0x3fb8aa3b, v215
	v_fma_f32 v139, v121, v139, 1.0
	v_exp_f32_e32 v215, v215
	v_mul_f32_e32 v139, v170, v139
	v_mul_f32_e32 v157, v131, v131
	v_mul_f32_e32 v175, v169, v139
	v_mul_f32_e32 v148, v147, v215
	v_mul_f32_e32 v165, v122, v175
	v_mul_f32_e32 v169, v169, v148
	ds_write_b32 v166, v169 offset:19312
	v_rcp_f32_e32 v176, v148
	s_nop 0
	v_mul_f32_e32 v139, v139, v176
	v_mul_f32_e32 v214, v214, v176
	v_mul_f32_e32 v176, v176, v215
	ds_write_b32 v166, v139 offset:54128
	v_mul_f32_e32 v138, v138, v176
	v_mul_f32_e32 v212, v212, v176
	v_mul_f32_e32 v176, v176, v213
	ds_write_b32 v166, v138 offset:53856
	v_mul_f32_e32 v137, v137, v176
	v_mul_f32_e32 v210, v210, v176
	v_mul_f32_e32 v176, v176, v211
	ds_write_b32 v166, v137 offset:53584
	v_mul_f32_e32 v136, v136, v176
	v_mul_f32_e32 v208, v208, v176
	v_mul_f32_e32 v176, v176, v209
	ds_write_b32 v166, v136 offset:53312
	v_mul_f32_e32 v135, v135, v176
	v_mul_f32_e32 v206, v206, v176
	v_mul_f32_e32 v176, v176, v207
	ds_write_b32 v166, v135 offset:53040
	v_mul_f32_e32 v134, v134, v176
	v_mul_f32_e32 v204, v204, v176
	v_mul_f32_e32 v176, v176, v205
	ds_write_b32 v166, v134 offset:52768
	v_mul_f32_e32 v133, v133, v176
	v_mul_f32_e32 v202, v202, v176
	v_mul_f32_e32 v176, v176, v203
	ds_write_b32 v166, v133 offset:52496
	v_mul_f32_e32 v132, v132, v176
	v_mul_f32_e32 v200, v200, v176
	ds_write_b32 v166, v132 offset:52224
	v_permlane32_swap_b32_e32 v150, v151
	v_permlane32_swap_b32_e32 v152, v153
	v_permlane32_swap_b32_e32 v154, v155
	v_permlane32_swap_b32_e32 v156, v157
	v_permlane32_swap_b32_e32 v158, v159
	v_permlane32_swap_b32_e32 v160, v161
	v_permlane32_swap_b32_e32 v162, v163
	v_permlane32_swap_b32_e32 v164, v165
	v_add_f32_e32 v182, v150, v151
	v_add_f32_e32 v183, v152, v153
	v_add_f32_e32 v184, v154, v155
	v_add_f32_e32 v185, v156, v157
	v_add_f32_e32 v186, v158, v159
	v_add_f32_e32 v187, v160, v161
	v_add_f32_e32 v188, v162, v163
	v_add_f32_e32 v189, v164, v165
	v_permlane16_swap_b32_e32 v182, v183
	v_permlane16_swap_b32_e32 v184, v185
	v_permlane16_swap_b32_e32 v186, v187
	v_permlane16_swap_b32_e32 v188, v189
	v_add_f32_e32 v190, v182, v183
	v_add_f32_e32 v191, v184, v185
	v_add_f32_e32 v192, v186, v187
	v_add_f32_e32 v193, v188, v189
	v_add_f32_dpp v194, v190, v190 row_mirror row_mask:0xf bank_mask:0x3
	v_add_f32_dpp v194, v191, v191 row_mirror row_mask:0xf bank_mask:0xc
	v_add_f32_dpp v195, v192, v192 row_mirror row_mask:0xf bank_mask:0x3
	v_add_f32_dpp v195, v193, v193 row_mirror row_mask:0xf bank_mask:0xc
	v_add_f32_dpp v196, v194, v194 row_half_mirror row_mask:0xf bank_mask:0x5
	s_nop 0
	v_add_f32_dpp v196, v195, v195 row_half_mirror row_mask:0xf bank_mask:0xa
	s_nop 1
	v_add_f32_dpp v196, v196, v196 quad_perm:[1,0,3,2] row_mask:0xf bank_mask:0xf
	s_nop 1
	v_add_f32_dpp v196, v196, v196 quad_perm:[2,3,0,1] row_mask:0xf bank_mask:0xf
	v_add_f32_e32 v197, 0x2b8cbccc, v196
	v_lshrrev_b32_e32 v198, 4, v76
	v_rsq_f32_e32 v197, v197
	v_bfe_u32 v168, v76, 3, 1
	v_lshl_add_u32 v198, v168, 2, v198
	v_add_u32_e32 v198, v198, v26
	v_lshl_add_u32 v198, v198, 2, s16
	s_mov_b32 s4, 0x10101010
	s_mov_b32 s5, 0x10101010
	s_mov_b64 exec, s[4:5]
	ds_write_b32 v198, v196
	s_mov_b64 exec, -1
	v_readlane_b32 s0, v197, 0
	v_readlane_b32 s1, v197, 16
	v_readlane_b32 s3, v197, 32
	v_readlane_b32 s4, v197, 48
	v_mul_f32_e32 v124, s0, v124
	v_mul_f32_e32 v125, s1, v125
	v_mul_f32_e32 v126, s3, v126
	v_mul_f32_e32 v127, s4, v127
	v_mul_f32_e64 v169, v124, -v140
	v_mul_f32_e32 v200, v124, v200
	v_mul_f32_e64 v170, v125, -v141
	v_mul_f32_e32 v202, v125, v202
	v_mul_f32_e64 v171, v126, -v142
	v_mul_f32_e32 v204, v126, v204
	v_mul_f32_e64 v172, v127, -v143
	v_mul_f32_e32 v206, v127, v206
	ds_write_b32 v166, v169 offset:0
	ds_write_b32 v166, v200 offset:34816
	ds_write_b32 v166, v170 offset:272
	ds_write_b32 v166, v202 offset:35088
	ds_write_b32 v166, v171 offset:544
	ds_write_b32 v166, v204 offset:35360
	ds_write_b32 v166, v172 offset:816
	ds_write_b32 v166, v206 offset:35632
	v_readlane_b32 s0, v197, 8
	v_readlane_b32 s1, v197, 24
	v_readlane_b32 s3, v197, 40
	v_readlane_b32 s4, v197, 56
	v_mul_f32_e32 v128, s0, v128
	v_mul_f32_e32 v129, s1, v129
	v_mul_f32_e32 v130, s3, v130
	v_mul_f32_e32 v131, s4, v131
	v_mul_f32_e64 v169, v128, -v144
	v_mul_f32_e32 v208, v128, v208
	v_mul_f32_e64 v170, v129, -v145
	v_mul_f32_e32 v210, v129, v210
	v_mul_f32_e64 v171, v130, -v146
	v_mul_f32_e32 v212, v130, v212
	v_mul_f32_e64 v172, v131, -v147
	v_mul_f32_e32 v214, v131, v214
	ds_write_b32 v166, v169 offset:1088
	ds_write_b32 v166, v208 offset:35904
	ds_write_b32 v166, v170 offset:1360
	ds_write_b32 v166, v210 offset:36176
	ds_write_b32 v166, v171 offset:1632
	ds_write_b32 v166, v212 offset:36448
	ds_write_b32 v166, v172 offset:1904
	ds_write_b32 v166, v214 offset:36720
	v_lshlrev_b32_e32 v168, 8, v78
	v_lshl_add_u32 v168, v76, 2, v168
	v_add_u32_e32 v168, 0x11000, v168
	ds_write_b32 v168, v148
	ds_read_b128 v[136:139], v79 offset:0
	ds_read_b128 v[152:155], v79 offset:34816
	ds_read_b128 v[140:143], v79 offset:64
	ds_read_b128 v[156:159], v79 offset:34880
	ds_read_b128 v[144:147], v79 offset:128
	ds_read_b128 v[160:163], v79 offset:34944
	ds_read_b128 v[148:151], v79 offset:192
	ds_read_b128 v[164:167], v79 offset:35008
	v_cmp_ge_u32_e64 s[0:1], 1, v87
	v_cmp_ge_u32_e64 s[4:5], 2, v87
	v_cmp_ge_u32_e64 s[6:7], 3, v87
	v_cmp_ge_u32_e32 vcc, 0, v87
	s_waitcnt lgkmcnt(0)
	v_mfma_f32_16x16x4_f32 v[36:39], v136, v152, 0
	v_mfma_f32_16x16x4_f32 v[40:43], v137, v153, 0
	v_mfma_f32_16x16x4_f32 v[36:39], v138, v154, v[36:39]
	v_mfma_f32_16x16x4_f32 v[40:43], v139, v155, v[40:43]
	v_mfma_f32_16x16x4_f32 v[36:39], v140, v156, v[36:39]
	v_mfma_f32_16x16x4_f32 v[40:43], v141, v157, v[40:43]
	v_mfma_f32_16x16x4_f32 v[36:39], v142, v158, v[36:39]
	v_mfma_f32_16x16x4_f32 v[40:43], v143, v159, v[40:43]
	v_mfma_f32_16x16x4_f32 v[36:39], v144, v160, v[36:39]
	v_mfma_f32_16x16x4_f32 v[40:43], v145, v161, v[40:43]
	v_mfma_f32_16x16x4_f32 v[36:39], v146, v162, v[36:39]
	v_mfma_f32_16x16x4_f32 v[40:43], v147, v163, v[40:43]
	v_mfma_f32_16x16x4_f32 v[36:39], v148, v164, v[36:39]
	v_mfma_f32_16x16x4_f32 v[40:43], v149, v165, v[40:43]
	v_mfma_f32_16x16x4_f32 v[36:39], v150, v166, v[36:39]
	v_mfma_f32_16x16x4_f32 v[40:43], v151, v167, v[40:43]
	s_nop 7
	s_nop 2
	v_pk_add_f32 v[36:37], v[36:37], v[40:41]
	v_pk_add_f32 v[38:39], v[38:39], v[42:43]
	v_cndmask_b32_e32 v36, 0, v36, vcc
	v_cndmask_b32_e64 v37, 0, v37, s[0:1]
	v_cndmask_b32_e64 v38, 0, v38, s[4:5]
	v_cndmask_b32_e64 v39, 0, v39, s[6:7]
	ds_write_b32 v86, v36 offset:0
	ds_write_b32 v86, v37 offset:32
	ds_write_b32 v86, v38 offset:64
	ds_write_b32 v86, v39 offset:96
	ds_read_b128 v[124:127], v92 offset:32
	ds_read_b128 v[128:131], v92 offset:64
	ds_read_b128 v[132:135], v92 offset:96
	ds_read_b128 v[136:139], v92 offset:128
	ds_read_b128 v[144:147], v92 offset:160
	ds_read_b128 v[148:151], v92 offset:176
	ds_read_b128 v[152:155], v92 offset:192
	ds_read_b128 v[156:159], v92 offset:208
	ds_read_b128 v[160:163], v92 offset:224
	ds_read_b128 v[164:167], v92 offset:240
	ds_read_b128 v[182:185], v93 offset:512
	ds_read_b128 v[186:189], v93 offset:528
	ds_read_b128 v[190:193], v93 offset:544
	ds_read_b128 v[194:197], v93 offset:560
	v_cmp_eq_u32_e32 vcc, 0, v102
	v_cndmask_b32_e32 v36, 0, v103, vcc
	v_cmp_eq_u32_e32 vcc, 1, v102
	v_cndmask_b32_e32 v37, 0, v103, vcc
	v_cmp_eq_u32_e32 vcc, 2, v102
	v_cndmask_b32_e32 v38, 0, v103, vcc
	v_cmp_eq_u32_e32 vcc, 3, v102
	v_cndmask_b32_e32 v39, 0, v103, vcc
	v_cmp_eq_u32_e32 vcc, 4, v102
	v_cndmask_b32_e32 v40, 0, v103, vcc
	v_cmp_eq_u32_e32 vcc, 5, v102
	v_cndmask_b32_e32 v41, 0, v103, vcc
	v_cmp_eq_u32_e32 vcc, 6, v102
	v_cndmask_b32_e32 v42, 0, v103, vcc
	v_cmp_eq_u32_e32 vcc, 7, v102
	v_cndmask_b32_e32 v43, 0, v103, vcc
	s_waitcnt lgkmcnt(0)
	v_fmac_f32_e32 v37, v124, v36
	v_fmac_f32_e32 v38, v128, v36
	v_fmac_f32_e32 v39, v132, v36
	v_fmac_f32_e32 v40, v136, v36
	v_fmac_f32_e32 v41, v144, v36
	v_fmac_f32_e32 v42, v152, v36
	v_fmac_f32_e32 v43, v160, v36
	v_fmac_f32_e32 v38, v129, v37
	v_fmac_f32_e32 v39, v133, v37
	v_fmac_f32_e32 v40, v137, v37
	v_fmac_f32_e32 v41, v145, v37
	v_fmac_f32_e32 v42, v153, v37
	v_fmac_f32_e32 v43, v161, v37
	v_fmac_f32_e32 v39, v134, v38
	v_fmac_f32_e32 v40, v138, v38
	v_fmac_f32_e32 v41, v146, v38
	v_fmac_f32_e32 v42, v154, v38
	v_fmac_f32_e32 v43, v162, v38
	v_fmac_f32_e32 v40, v139, v39
	v_fmac_f32_e32 v41, v147, v39
	v_fmac_f32_e32 v42, v155, v39
	v_fmac_f32_e32 v43, v163, v39
	v_fmac_f32_e32 v41, v148, v40
	v_fmac_f32_e32 v42, v156, v40
	v_fmac_f32_e32 v43, v164, v40
	v_fmac_f32_e32 v42, v157, v41
	v_fmac_f32_e32 v43, v165, v41
	v_fmac_f32_e32 v43, v166, v42
	v_mul_f32_e32 v198, v182, v36
	v_fmac_f32_e32 v198, v183, v37
	v_fmac_f32_e32 v198, v184, v38
	v_fmac_f32_e32 v198, v185, v39
	v_fmac_f32_e32 v198, v186, v40
	v_fmac_f32_e32 v198, v187, v41
	v_fmac_f32_e32 v198, v188, v42
	v_fmac_f32_e32 v198, v189, v43
	v_mul_f32_e32 v199, v190, v36
	v_fmac_f32_e32 v199, v191, v37
	v_fmac_f32_e32 v199, v192, v38
	v_fmac_f32_e32 v199, v193, v39
	v_fmac_f32_e32 v199, v194, v40
	v_fmac_f32_e32 v199, v195, v41
	v_fmac_f32_e32 v199, v196, v42
	v_fmac_f32_e32 v199, v197, v43
	ds_write_b32 v100, v36 offset:0
	ds_write_b32 v100, v37 offset:32
	ds_write_b32 v100, v38 offset:64
	ds_write_b32 v100, v39 offset:96
	ds_write_b32 v100, v40 offset:128
	ds_write_b32 v100, v41 offset:160
	ds_write_b32 v100, v42 offset:192
	ds_write_b32 v100, v43 offset:224
	ds_write_b32 v101, v198 offset:512
	ds_write_b32 v101, v199 offset:544
	s_lshl_b32 s17, s40, 6
	s_cmp_lg_u32 s40, 31
	s_waitcnt lgkmcnt(0)
	s_barrier
	s_cbranch_scc0 .LBB0_586
	v_readfirstlane_b32 s0, v180
	s_nop 1
	s_cmpk_ge_u32 s0, 0x100
	s_cbranch_scc1 .LBB0_586
	v_readfirstlane_b32 s0, v78
	v_lshlrev_b32_e32 v2, 1, v28
	v_lshlrev_b32_e32 v3, 2, v28
	s_lshl_b32 s0, s0, 3
	s_add_i32 s0, s0, s17
	s_add_i32 s0, s0, 64
	s_add_u32 s0, s80, s0
	s_mul_i32 s1, s0, s83
	s_add_u32 s4, s46, s1
	s_addc_u32 s5, s47, 0
	s_lshl_b32 s1, s0, 10
	s_add_u32 s6, s62, s1
	s_addc_u32 s7, s63, 0
	s_lshl_b32 s1, s0, 11
	s_add_u32 s10, s34, s1
	s_addc_u32 s11, s35, 0
	global_load_short_d16_hi v106, v2, s[4:5] offset:-3072
	global_load_short_d16_hi v35, v2, s[4:5] offset:-2048
	global_load_short_d16_hi v34, v2, s[4:5] offset:-1024
	global_load_short_d16_hi v44, v2, s[4:5]
	global_load_short_d16_hi v46, v2, s[4:5] offset:1024
	global_load_short_d16_hi v48, v2, s[4:5] offset:2048
	s_add_u32 s4, s4, s83
	s_addc_u32 s5, s5, 0
	global_load_short_d16_hi v50, v2, s[6:7]
	global_load_dword v107, v3, s[10:11]
	global_load_short_d16_hi v1, v2, s[4:5]
	global_load_short_d16_hi v45, v2, s[4:5] offset:1024
	global_load_short_d16_hi v47, v2, s[4:5] offset:2048
	s_add_u32 s4, s4, s83
	s_addc_u32 s5, s5, 0
	global_load_short_d16_hi v51, v2, s[6:7] offset:1024
	global_load_dword v108, v3, s[10:11] offset:2048
	s_add_u32 s10, s10, 0x1000
	s_addc_u32 s11, s11, 0
	global_load_short_d16_hi v52, v2, s[4:5]
	global_load_short_d16_hi v54, v2, s[4:5] offset:1024
	global_load_short_d16_hi v56, v2, s[4:5] offset:2048
	s_add_u32 s4, s4, s83
	s_addc_u32 s5, s5, 0
	global_load_short_d16_hi v58, v2, s[6:7] offset:2048
	global_load_dword v109, v3, s[10:11]
	global_load_short_d16_hi v49, v2, s[4:5]
	global_load_short_d16_hi v53, v2, s[4:5] offset:1024
	global_load_short_d16_hi v55, v2, s[4:5] offset:2048
	s_add_u32 s4, s4, s83
	s_addc_u32 s5, s5, 0
	global_load_short_d16_hi v57, v2, s[6:7] offset:3072
	s_add_u32 s6, s6, 0x1000
	s_addc_u32 s7, s7, 0
	global_load_dword v110, v3, s[10:11] offset:2048
	s_add_u32 s10, s10, 0x1000
	s_addc_u32 s11, s11, 0
	global_load_short_d16_hi v60, v2, s[4:5]
	global_load_short_d16_hi v62, v2, s[4:5] offset:1024
	global_load_short_d16_hi v64, v2, s[4:5] offset:2048
	s_add_u32 s4, s4, s83
	s_addc_u32 s5, s5, 0
	global_load_short_d16_hi v66, v2, s[6:7]
	global_load_dword v111, v3, s[10:11]
	global_load_short_d16_hi v59, v2, s[4:5]
	global_load_short_d16_hi v61, v2, s[4:5] offset:1024
	global_load_short_d16_hi v63, v2, s[4:5] offset:2048
	s_add_u32 s4, s4, s83
	s_addc_u32 s5, s5, 0
	global_load_short_d16_hi v65, v2, s[6:7] offset:1024
	global_load_dword v112, v3, s[10:11] offset:2048
	s_add_u32 s10, s10, 0x1000
	s_addc_u32 s11, s11, 0
	global_load_short_d16_hi v67, v2, s[4:5]
	global_load_short_d16_hi v69, v2, s[4:5] offset:1024
	global_load_short_d16_hi v71, v2, s[4:5] offset:2048
	s_add_u32 s4, s4, s83
	s_addc_u32 s5, s5, 0
	global_load_short_d16_hi v74, v2, s[6:7] offset:2048
	global_load_dword v113, v3, s[10:11]
	global_load_short_d16_hi v68, v2, s[4:5]
	global_load_short_d16_hi v70, v2, s[4:5] offset:1024
	global_load_short_d16_hi v72, v2, s[4:5] offset:2048
	global_load_short_d16_hi v73, v2, s[6:7] offset:3072
	global_load_dword v114, v3, s[10:11] offset:2048
